# hyena: skip re-zeroing of LDS pads when previous unit in block had same path
# baseline (speedup 1.0000x reference)
.LBB0_357:
	s_mov_b32 s98, 0
	s_cmp_gt_i32 s87, 3
	s_cbranch_scc1 .LBB0_730
	s_load_dword s0, s[92:93], 0x104
	s_waitcnt lgkmcnt(0)
	s_cmp_lt_i32 s0, 4
	s_cbranch_scc1 .LBB0_730
	s_cmp_eq_u32 s87, 3
	s_cbranch_scc0 .LBB0_362
	s_cmpk_lg_i32 s94, 0x100
	s_mov_b64 s[0:1], -1
	s_cbranch_scc1 .LBB0_429

.LBB0_612:
	s_or_b64 exec, exec, s[0:1]
	v_cmp_gt_i32_e32 vcc, s28, v22
	s_and_saveexec_b64 s[0:1], vcc
	s_cbranch_execz .LBB0_624
	s_cmp_eq_u32 s98, 1
	s_cbranch_scc1 .LBB0_624
	v_max_i32_e32 v15, 0x240, v22
	v_sub_u32_e32 v15, v15, v22
	v_add_u32_e32 v15, 0x1ff, v15
	v_cmp_lt_u32_e32 vcc, s29, v15
	s_mov_b64 s[4:5], -1
	v_mov_b32_e32 v16, v22
	s_and_saveexec_b64 s[2:3], vcc
	s_cbranch_execz .LBB0_621
	v_lshrrev_b32_e32 v15, 9, v15
	v_add_u32_e32 v25, 0x600, v22
	v_add_u32_e32 v24, 0x400, v22
	v_add_u32_e32 v23, 0x200, v22
	v_add_u32_e32 v16, -3, v15
	v_mov_b64_e32 v[28:29], v[24:25]
	v_cmp_lt_u32_e32 vcc, 3, v16
	v_mov_b64_e32 v[26:27], v[22:23]
	s_and_saveexec_b64 s[18:19], vcc
	s_cbranch_execz .LBB0_618
	v_lshrrev_b32_e32 v17, 2, v16
	v_add_u32_e32 v17, 1, v17
	v_mov_b64_e32 v[28:29], v[24:25]
	v_and_b32_e32 v17, 0x7ffffffe, v17
	s_mov_b64 s[20:21], 0
	v_mov_b64_e32 v[26:27], v[22:23]

.LBB0_626:
	s_or_b64 exec, exec, s[0:1]
	v_cmp_gt_i32_e32 vcc, s42, v22
	s_and_saveexec_b64 s[0:1], vcc
	s_cbranch_execz .LBB0_638
	s_cmp_eq_u32 s98, 1
	s_cbranch_scc1 .LBB0_638
	v_max_i32_e32 v15, 32, v22
	v_sub_u32_e32 v15, v15, v22
	v_add_u32_e32 v15, 0x1ff, v15
	v_cmp_lt_u32_e32 vcc, s29, v15
	s_mov_b64 s[4:5], -1
	v_mov_b32_e32 v16, v22
	s_and_saveexec_b64 s[2:3], vcc
	s_cbranch_execz .LBB0_635
	v_lshrrev_b32_e32 v15, 9, v15
	v_add_u32_e32 v25, 0x600, v22
	v_add_u32_e32 v24, 0x400, v22
	v_add_u32_e32 v23, 0x200, v22
	v_add_u32_e32 v16, -3, v15
	v_mov_b64_e32 v[28:29], v[24:25]
	v_cmp_lt_u32_e32 vcc, 3, v16
	v_mov_b64_e32 v[26:27], v[22:23]
	s_and_saveexec_b64 s[4:5], vcc
	s_cbranch_execz .LBB0_632
	v_lshrrev_b32_e32 v17, 2, v16
	v_add_u32_e32 v17, 1, v17
	v_mov_b64_e32 v[28:29], v[24:25]
	v_and_b32_e32 v17, 0x7ffffffe, v17
	s_mov_b64 s[6:7], 0
	v_mov_b64_e32 v[26:27], v[22:23]

.LBB0_638:
	s_or_b64 exec, exec, s[0:1]
	s_mov_b32 s98, 1
	v_lshlrev_b32_e32 v23, 1, v22
	v_and_b32_e32 v15, 15, v22
	v_and_b32_e32 v24, 0xffffff80, v23
	v_and_b32_e32 v23, 1, v22
	v_lshlrev_b32_e32 v26, 2, v22
	v_bfe_u32 v16, v22, 4, 2
	v_and_b32_e32 v17, 3, v22
	v_add_u32_e32 v15, v15, v23
	v_and_b32_e32 v26, 48, v26
	v_lshlrev_b32_e32 v25, 3, v16
	v_or_b32_e32 v15, v15, v24
	v_mad_u32_u24 v27, v17, s40, v26
	v_sub_u32_e32 v15, v25, v15
	v_add_lshl_u32 v99, v27, v25, 1
	v_lshlrev_b32_e32 v16, 2, v16
	v_lshlrev_b32_e32 v25, 10, v17
	v_lshl_add_u32 v15, v15, 1, v92
	v_or3_b32 v24, v16, v24, v26
	v_or_b32_e32 v26, 0x1000, v25
	v_and_b32_e32 v15, -4, v15
	s_lshl_b32 s2, s16, 1
	v_add_u32_e32 v16, v24, v26
	v_add_u32_e32 v98, 0, v15
	v_mad_u32_u24 v15, v17, s40, 64
	s_add_u32 s2, s22, s2
	v_ashrrev_i32_e32 v17, 31, v16
	s_addc_u32 s3, s23, 0
	v_lshlrev_b64 v[16:17], 11, v[16:17]
	s_waitcnt lgkmcnt(0)
	s_barrier
	v_lshl_add_u64 v[68:69], s[2:3], 0, v[16:17]
	v_or_b32_e32 v16, 64, v24
	s_load_dwordx2 s[0:1], s[92:93], 0xb0
	v_add_lshl_u32 v102, v16, v15, 1
	v_add_lshl_u32 v103, v16, v25, 1
	v_add_u32_e32 v16, v16, v26
	v_ashrrev_i32_e32 v17, 31, v16
	v_lshlrev_b64 v[16:17], 11, v[16:17]
	v_add_lshl_u32 v100, v24, v15, 1
	v_add_lshl_u32 v101, v24, v25, 1
	v_lshl_add_u64 v[74:75], s[2:3], 0, v[16:17]
	v_mov_b64_e32 v[38:39], v[20:21]
	v_mov_b64_e32 v[34:35], v[12:13]
	v_mov_b64_e32 v[30:31], v[8:9]
	v_mov_b64_e32 v[26:27], v[4:5]
	v_lshl_add_u64 v[70:71], v[68:69], 0, s[12:13]
	v_lshl_add_u64 v[72:73], v[68:69], 0, s[14:15]
	v_lshl_add_u64 v[76:77], v[74:75], 0, s[12:13]
	v_lshl_add_u64 v[78:79], v[74:75], 0, s[14:15]
	s_mov_b32 s8, 0
	s_mov_b64 s[4:5], -1
	s_mov_b32 s17, -1
	v_mov_b64_e32 v[36:37], v[18:19]
	v_mov_b32_e32 v106, v84
	v_mov_b32_e32 v104, v82
	v_mov_b32_e32 v96, v80
	v_mov_b32_e32 v107, v83
	v_mov_b32_e32 v105, v81
	v_mov_b32_e32 v97, v1
	v_mov_b64_e32 v[32:33], v[10:11]
	v_mov_b64_e32 v[28:29], v[6:7]
	v_mov_b64_e32 v[24:25], v[2:3]
	s_branch .LBB0_641

.LBB0_673:
	s_or_b64 exec, exec, s[0:1]
	v_cmp_gt_i32_e32 vcc, s47, v22
	s_and_saveexec_b64 s[0:1], vcc
	s_cbranch_execz .LBB0_685
	s_cmp_eq_u32 s98, 2
	s_cbranch_scc1 .LBB0_685
	v_max_i32_e32 v15, 0xf00, v22
	v_sub_u32_e32 v15, v15, v22
	v_add_u32_e32 v15, 0x1ff, v15
	v_cmp_lt_u32_e32 vcc, s29, v15
	s_mov_b64 s[4:5], -1
	v_mov_b32_e32 v16, v22
	s_and_saveexec_b64 s[2:3], vcc
	s_cbranch_execz .LBB0_682
	v_lshrrev_b32_e32 v15, 9, v15
	s_waitcnt vmcnt(2)
	v_add_u32_e32 v25, 0x600, v22
	v_add_u32_e32 v24, 0x400, v22
	v_add_u32_e32 v23, 0x200, v22
	v_add_u32_e32 v16, -3, v15
	s_waitcnt vmcnt(1)
	v_mov_b64_e32 v[28:29], v[24:25]
	v_cmp_lt_u32_e32 vcc, 3, v16
	v_mov_b64_e32 v[26:27], v[22:23]
	s_and_saveexec_b64 s[18:19], vcc
	s_cbranch_execz .LBB0_679
	v_lshrrev_b32_e32 v17, 2, v16
	v_add_u32_e32 v17, 1, v17
	v_mov_b64_e32 v[28:29], v[24:25]
	v_and_b32_e32 v17, 0x7ffffffe, v17
	s_mov_b64 s[20:21], 0
	v_mov_b64_e32 v[26:27], v[22:23]

.LBB0_687:
	s_or_b64 exec, exec, s[0:1]
	v_cmp_gt_i32_e32 vcc, s42, v22
	s_and_saveexec_b64 s[0:1], vcc
	s_cbranch_execz .LBB0_699
	s_cmp_eq_u32 s98, 2
	s_cbranch_scc1 .LBB0_699
	v_max_i32_e32 v15, 32, v22
	v_sub_u32_e32 v15, v15, v22
	v_add_u32_e32 v15, 0x1ff, v15
	v_cmp_lt_u32_e32 vcc, s29, v15
	s_mov_b64 s[4:5], -1
	v_mov_b32_e32 v16, v22
	s_and_saveexec_b64 s[2:3], vcc
	s_cbranch_execz .LBB0_696
	v_lshrrev_b32_e32 v15, 9, v15
	v_add_u32_e32 v25, 0x600, v22
	v_add_u32_e32 v24, 0x400, v22
	v_add_u32_e32 v23, 0x200, v22
	v_add_u32_e32 v16, -3, v15
	v_mov_b64_e32 v[28:29], v[24:25]
	v_cmp_lt_u32_e32 vcc, 3, v16
	v_mov_b64_e32 v[26:27], v[22:23]
	s_and_saveexec_b64 s[4:5], vcc
	s_cbranch_execz .LBB0_693
	v_lshrrev_b32_e32 v17, 2, v16
	v_add_u32_e32 v17, 1, v17
	v_mov_b64_e32 v[28:29], v[24:25]
	v_and_b32_e32 v17, 0x7ffffffe, v17
	s_mov_b64 s[6:7], 0
	v_mov_b64_e32 v[26:27], v[22:23]

.LBB0_699:
	s_or_b64 exec, exec, s[0:1]
	s_mov_b32 s98, 2
	v_and_b32_e32 v15, 15, v22
	v_ashrrev_i32_e32 v17, 1, v22
	v_and_b32_e32 v23, 1, v22
	v_bfe_u32 v16, v22, 4, 2
	v_and_b32_e32 v17, 0xffffffe0, v17
	v_add_u32_e32 v25, v15, v23
	v_lshlrev_b32_e32 v24, 3, v16
	v_or_b32_e32 v25, v17, v25
	v_mad_u32_u24 v26, v15, s52, 64
	v_sub_u32_e32 v25, v24, v25
	v_add_lshl_u32 v45, v26, v24, 1
	v_lshl_or_b32 v24, v16, 2, v17
	v_lshlrev_b32_e32 v15, 8, v15
	s_lshl_b32 s2, s16, 1
	v_add_u32_e32 v16, v24, v15
	s_add_u32 s2, s22, s2
	v_ashrrev_i32_e32 v17, 31, v16
	s_addc_u32 s3, s23, 0
	v_lshlrev_b32_e32 v47, 1, v16
	v_lshlrev_b64 v[16:17], 11, v[16:17]
	s_waitcnt lgkmcnt(0)
	s_barrier
	v_lshl_add_u64 v[32:33], s[2:3], 0, v[16:17]
	v_or_b32_e32 v16, 16, v24
	s_load_dwordx2 s[0:1], s[92:93], 0xb0
	v_add_lshl_u32 v48, v16, v26, 1
	v_add_u32_e32 v16, v16, v15
	v_ashrrev_i32_e32 v17, 31, v16
	v_lshlrev_b32_e32 v49, 1, v16
	v_lshlrev_b64 v[16:17], 11, v[16:17]
	v_lshl_add_u32 v15, v25, 1, v94
	v_lshl_add_u64 v[38:39], s[2:3], 0, v[16:17]
	v_and_b32_e32 v15, -4, v15
	v_add_lshl_u32 v46, v24, v26, 1
	v_lshl_add_u64 v[34:35], v[32:33], 0, s[12:13]
	v_lshl_add_u64 v[36:37], v[32:33], 0, s[14:15]
	v_lshl_add_u64 v[40:41], v[38:39], 0, s[12:13]
	v_lshl_add_u64 v[42:43], v[38:39], 0, s[14:15]
	v_add_u32_e32 v50, s56, v15
	s_mov_b32 s8, 0
	s_mov_b64 s[4:5], -1
	s_mov_b32 s17, -1
	s_branch .LBB0_702

.LBB0_1598:
	s_mov_b32 s98, 0
	s_cmp_gt_i32 s87, 13
	s_cbranch_scc1 .LBB0_1971
	s_load_dword s0, s[92:93], 0x104
	s_waitcnt lgkmcnt(0)
	s_cmp_lt_i32 s0, 14
	s_cbranch_scc1 .LBB0_1971
	s_cmp_eq_u32 s87, 13
	s_cbranch_scc0 .LBB0_1603
	s_cmpk_lg_i32 s94, 0x100
	s_mov_b64 s[0:1], -1
	s_cbranch_scc1 .LBB0_1670

.LBB0_1853:
	s_or_b64 exec, exec, s[0:1]
	v_cmp_gt_i32_e32 vcc, s30, v22
	s_and_saveexec_b64 s[0:1], vcc
	s_cbranch_execz .LBB0_1865
	s_cmp_eq_u32 s98, 1
	s_cbranch_scc1 .LBB0_1865
	v_max_i32_e32 v15, 0x240, v22
	v_sub_u32_e32 v15, v15, v22
	v_add_u32_e32 v15, 0x1ff, v15
	v_cmp_lt_u32_e32 vcc, s31, v15
	s_mov_b64 s[4:5], -1
	v_mov_b32_e32 v16, v22
	s_and_saveexec_b64 s[2:3], vcc
	s_cbranch_execz .LBB0_1862
	v_lshrrev_b32_e32 v15, 9, v15
	v_add_u32_e32 v25, 0x600, v22
	v_add_u32_e32 v24, 0x400, v22
	v_add_u32_e32 v23, 0x200, v22
	v_add_u32_e32 v16, -3, v15
	v_mov_b64_e32 v[28:29], v[24:25]
	v_cmp_lt_u32_e32 vcc, 3, v16
	v_mov_b64_e32 v[26:27], v[22:23]
	s_and_saveexec_b64 s[20:21], vcc
	s_cbranch_execz .LBB0_1859
	v_lshrrev_b32_e32 v17, 2, v16
	v_add_u32_e32 v17, 1, v17
	v_mov_b64_e32 v[28:29], v[24:25]
	v_and_b32_e32 v17, 0x7ffffffe, v17
	s_mov_b64 s[22:23], 0
	v_mov_b64_e32 v[26:27], v[22:23]

.LBB0_1867:
	s_or_b64 exec, exec, s[0:1]
	v_cmp_gt_i32_e32 vcc, s44, v22
	s_and_saveexec_b64 s[0:1], vcc
	s_cbranch_execz .LBB0_1879
	s_cmp_eq_u32 s98, 1
	s_cbranch_scc1 .LBB0_1879
	v_max_i32_e32 v15, 32, v22
	v_sub_u32_e32 v15, v15, v22
	v_add_u32_e32 v15, 0x1ff, v15
	v_cmp_lt_u32_e32 vcc, s31, v15
	s_mov_b64 s[4:5], -1
	v_mov_b32_e32 v16, v22
	s_and_saveexec_b64 s[2:3], vcc
	s_cbranch_execz .LBB0_1876
	v_lshrrev_b32_e32 v15, 9, v15
	v_add_u32_e32 v25, 0x600, v22
	v_add_u32_e32 v24, 0x400, v22
	v_add_u32_e32 v23, 0x200, v22
	v_add_u32_e32 v16, -3, v15
	v_mov_b64_e32 v[28:29], v[24:25]
	v_cmp_lt_u32_e32 vcc, 3, v16
	v_mov_b64_e32 v[26:27], v[22:23]
	s_and_saveexec_b64 s[4:5], vcc
	s_cbranch_execz .LBB0_1873
	v_lshrrev_b32_e32 v17, 2, v16
	v_add_u32_e32 v17, 1, v17
	v_mov_b64_e32 v[28:29], v[24:25]
	v_and_b32_e32 v17, 0x7ffffffe, v17
	s_mov_b64 s[6:7], 0
	v_mov_b64_e32 v[26:27], v[22:23]

.LBB0_1879:
	s_or_b64 exec, exec, s[0:1]
	s_mov_b32 s98, 1
	v_lshlrev_b32_e32 v23, 1, v22
	v_and_b32_e32 v15, 15, v22
	v_and_b32_e32 v24, 0xffffff80, v23
	v_and_b32_e32 v23, 1, v22
	v_lshlrev_b32_e32 v26, 2, v22
	v_bfe_u32 v16, v22, 4, 2
	v_and_b32_e32 v17, 3, v22
	v_add_u32_e32 v15, v15, v23
	v_and_b32_e32 v26, 48, v26
	v_lshlrev_b32_e32 v25, 3, v16
	v_or_b32_e32 v15, v15, v24
	v_mad_u32_u24 v27, v17, s42, v26
	v_sub_u32_e32 v15, v25, v15
	v_add_lshl_u32 v106, v27, v25, 1
	v_lshlrev_b32_e32 v16, 2, v16
	v_lshlrev_b32_e32 v25, 10, v17
	v_lshl_add_u32 v15, v15, 1, v99
	v_or3_b32 v24, v16, v24, v26
	v_or_b32_e32 v26, 0x1000, v25
	v_and_b32_e32 v15, -4, v15
	s_lshl_b32 s2, s18, 1
	v_add_u32_e32 v16, v24, v26
	v_add_u32_e32 v105, 0, v15
	v_mad_u32_u24 v15, v17, s42, 64
	s_add_u32 s2, s24, s2
	v_ashrrev_i32_e32 v17, 31, v16
	s_addc_u32 s3, s25, 0
	v_lshlrev_b64 v[16:17], 11, v[16:17]
	s_waitcnt lgkmcnt(0)
	s_barrier
	v_lshl_add_u64 v[68:69], s[2:3], 0, v[16:17]
	v_or_b32_e32 v16, 64, v24
	s_load_dwordx2 s[0:1], s[92:93], 0xb0
	v_add_lshl_u32 v109, v16, v15, 1
	v_add_lshl_u32 v110, v16, v25, 1
	v_add_u32_e32 v16, v16, v26
	v_ashrrev_i32_e32 v17, 31, v16
	v_lshlrev_b64 v[16:17], 11, v[16:17]
	v_add_lshl_u32 v107, v24, v15, 1
	v_add_lshl_u32 v108, v24, v25, 1
	v_lshl_add_u64 v[74:75], s[2:3], 0, v[16:17]
	v_mov_b64_e32 v[38:39], v[20:21]
	v_mov_b64_e32 v[34:35], v[12:13]
	v_mov_b64_e32 v[30:31], v[8:9]
	v_mov_b64_e32 v[26:27], v[4:5]
	v_lshl_add_u64 v[70:71], v[68:69], 0, s[14:15]
	v_lshl_add_u64 v[72:73], v[68:69], 0, s[16:17]
	v_lshl_add_u64 v[76:77], v[74:75], 0, s[14:15]
	v_lshl_add_u64 v[78:79], v[74:75], 0, s[16:17]
	s_mov_b32 s8, 0
	s_mov_b64 s[4:5], -1
	s_mov_b32 s19, -1
	v_mov_b64_e32 v[36:37], v[18:19]
	v_mov_b32_e32 v113, v84
	v_mov_b32_e32 v111, v82
	v_mov_b32_e32 v103, v80
	v_mov_b32_e32 v114, v83
	v_mov_b32_e32 v112, v81
	v_mov_b32_e32 v104, v1
	v_mov_b64_e32 v[32:33], v[10:11]
	v_mov_b64_e32 v[28:29], v[6:7]
	v_mov_b64_e32 v[24:25], v[2:3]
	s_branch .LBB0_1882

.LBB0_1914:
	s_or_b64 exec, exec, s[0:1]
	v_cmp_gt_i32_e32 vcc, s49, v22
	s_and_saveexec_b64 s[0:1], vcc
	s_cbranch_execz .LBB0_1926
	s_cmp_eq_u32 s98, 2
	s_cbranch_scc1 .LBB0_1926
	v_max_i32_e32 v15, 0xf00, v22
	v_sub_u32_e32 v15, v15, v22
	v_add_u32_e32 v15, 0x1ff, v15
	v_cmp_lt_u32_e32 vcc, s31, v15
	s_mov_b64 s[4:5], -1
	v_mov_b32_e32 v16, v22
	s_and_saveexec_b64 s[2:3], vcc
	s_cbranch_execz .LBB0_1923
	v_lshrrev_b32_e32 v15, 9, v15
	s_waitcnt vmcnt(2)
	v_add_u32_e32 v25, 0x600, v22
	v_add_u32_e32 v24, 0x400, v22
	v_add_u32_e32 v23, 0x200, v22
	v_add_u32_e32 v16, -3, v15
	s_waitcnt vmcnt(1)
	v_mov_b64_e32 v[28:29], v[24:25]
	v_cmp_lt_u32_e32 vcc, 3, v16
	v_mov_b64_e32 v[26:27], v[22:23]
	s_and_saveexec_b64 s[20:21], vcc
	s_cbranch_execz .LBB0_1920
	v_lshrrev_b32_e32 v17, 2, v16
	v_add_u32_e32 v17, 1, v17
	v_mov_b64_e32 v[28:29], v[24:25]
	v_and_b32_e32 v17, 0x7ffffffe, v17
	s_mov_b64 s[22:23], 0
	v_mov_b64_e32 v[26:27], v[22:23]

.LBB0_1928:
	s_or_b64 exec, exec, s[0:1]
	v_cmp_gt_i32_e32 vcc, s44, v22
	s_and_saveexec_b64 s[0:1], vcc
	s_cbranch_execz .LBB0_1940
	s_cmp_eq_u32 s98, 2
	s_cbranch_scc1 .LBB0_1940
	v_max_i32_e32 v15, 32, v22
	v_sub_u32_e32 v15, v15, v22
	v_add_u32_e32 v15, 0x1ff, v15
	v_cmp_lt_u32_e32 vcc, s31, v15
	s_mov_b64 s[4:5], -1
	v_mov_b32_e32 v16, v22
	s_and_saveexec_b64 s[2:3], vcc
	s_cbranch_execz .LBB0_1937
	v_lshrrev_b32_e32 v15, 9, v15
	v_add_u32_e32 v25, 0x600, v22
	v_add_u32_e32 v24, 0x400, v22
	v_add_u32_e32 v23, 0x200, v22
	v_add_u32_e32 v16, -3, v15
	v_mov_b64_e32 v[28:29], v[24:25]
	v_cmp_lt_u32_e32 vcc, 3, v16
	v_mov_b64_e32 v[26:27], v[22:23]
	s_and_saveexec_b64 s[4:5], vcc
	s_cbranch_execz .LBB0_1934
	v_lshrrev_b32_e32 v17, 2, v16
	v_add_u32_e32 v17, 1, v17
	v_mov_b64_e32 v[28:29], v[24:25]
	v_and_b32_e32 v17, 0x7ffffffe, v17
	s_mov_b64 s[6:7], 0
	v_mov_b64_e32 v[26:27], v[22:23]

.LBB0_1940:
	s_or_b64 exec, exec, s[0:1]
	s_mov_b32 s98, 2
	v_and_b32_e32 v15, 15, v22
	v_ashrrev_i32_e32 v17, 1, v22
	v_and_b32_e32 v23, 1, v22
	v_bfe_u32 v16, v22, 4, 2
	v_and_b32_e32 v17, 0xffffffe0, v17
	v_add_u32_e32 v25, v15, v23
	v_lshlrev_b32_e32 v24, 3, v16
	v_or_b32_e32 v25, v17, v25
	v_mad_u32_u24 v26, v15, s54, 64
	v_sub_u32_e32 v25, v24, v25
	v_add_lshl_u32 v45, v26, v24, 1
	v_lshl_or_b32 v24, v16, 2, v17
	v_lshlrev_b32_e32 v15, 8, v15
	s_lshl_b32 s2, s18, 1
	v_add_u32_e32 v16, v24, v15
	s_add_u32 s2, s24, s2
	v_ashrrev_i32_e32 v17, 31, v16
	s_addc_u32 s3, s25, 0
	v_lshlrev_b32_e32 v47, 1, v16
	v_lshlrev_b64 v[16:17], 11, v[16:17]
	s_waitcnt lgkmcnt(0)
	s_barrier
	v_lshl_add_u64 v[32:33], s[2:3], 0, v[16:17]
	v_or_b32_e32 v16, 16, v24
	s_load_dwordx2 s[0:1], s[92:93], 0xb0
	v_add_lshl_u32 v48, v16, v26, 1
	v_add_u32_e32 v16, v16, v15
	v_ashrrev_i32_e32 v17, 31, v16
	v_lshlrev_b32_e32 v49, 1, v16
	v_lshlrev_b64 v[16:17], 11, v[16:17]
	v_lshl_add_u32 v15, v25, 1, v101
	v_lshl_add_u64 v[38:39], s[2:3], 0, v[16:17]
	v_and_b32_e32 v15, -4, v15
	v_add_lshl_u32 v46, v24, v26, 1
	v_lshl_add_u64 v[34:35], v[32:33], 0, s[14:15]
	v_lshl_add_u64 v[36:37], v[32:33], 0, s[16:17]
	v_lshl_add_u64 v[40:41], v[38:39], 0, s[14:15]
	v_lshl_add_u64 v[42:43], v[38:39], 0, s[16:17]
	v_add_u32_e32 v50, s58, v15
	s_mov_b32 s8, 0
	s_mov_b64 s[4:5], -1
	s_mov_b32 s19, -1
	s_branch .LBB0_1943
